# xs stores sc1 (write-through, not kept in L2) + de-serialised residual epilogue + MIDK batched + attention vmcnt ladder
# baseline (speedup 1.0000x reference)
; #define PG8_GAS __attribute__((address_space(1)))
; __device__ __forceinline__ unsigned cvtpk(float lo, float hi) { f32x2 v = {lo, hi}; bf16x2_t b = __builtin_convertvector(v, bf16x2_t); return __builtin_bit_cast(unsigned, b); }
; template <class T> __device__ __forceinline__ GAS T* gp(T* p) { return (GAS T*)p; }
;     __device__ __forceinline__ void operator()(const f32x4 (&acc)[2][2][4][2], const Unit& u, int wr, int wc, int fr, int fq) const {
;         const int b = (u.pm * BM) >> 13;
;         const float* gp = mod + b * 9216 + step * 3072 + 2048; const float coef = step == 1 ? 1.0f : 0.5f;
;         const float* basef = step == 0 ? xin : (const float*)nullptr; const bf16_t* baseb = xs; bf16_t* out = xs;
;         const int col0 = u.pn * BM + wc * 32 + 8 * fq;
;         f32x4 gv[2][2];
; #pragma unroll
;         for (int bj = 0; bj < 2; ++bj)
; #pragma unroll
;             for (int n = 0; n < 2; ++n) gv[bj][n] = (*(const PG8_GAS f32x4*)(gp + col0 + bj * HALF + 4 * n) + 1.0f) * coef;
; #pragma unroll
;         for (int ai = 0; ai < 2; ++ai)
; #pragma unroll
;             for (int m = 0; m < 4; ++m) {
;                 const size_t off = (size_t)(u.pm * BM + ai * HALF + wr * 64 + m * 16 + fr) * 1024 + col0;
; #pragma unroll
;                 for (int bj = 0; bj < 2; ++bj) {
;                     f32x4 b0, b1;
;                     if (basef) { b0 = __builtin_nontemporal_load((const PG8_GAS f32x4*)(basef + off + bj * HALF)); b1 = __builtin_nontemporal_load((const PG8_GAS f32x4*)(basef + off + bj * HALF + 4)); }
;                     else { const u32x4 w = __builtin_nontemporal_load((const PG8_GAS u32x4*)(baseb + off + bj * HALF));
;                         b0 = (f32x4){__uint_as_float(w.x << 16), __uint_as_float(w.x & 0xffff0000u), __uint_as_float(w.y << 16), __uint_as_float(w.y & 0xffff0000u)};
;                         b1 = (f32x4){__uint_as_float(w.z << 16), __uint_as_float(w.z & 0xffff0000u), __uint_as_float(w.w << 16), __uint_as_float(w.w & 0xffff0000u)}; }
;                     const f32x4 o0 = b0 + gv[bj][0] * acc[ai][bj][m][0], o1 = b1 + gv[bj][1] * acc[ai][bj][m][1];
;                     u32x4 w; w.x = cvtpk(o0[0], o0[1]); w.y = cvtpk(o0[2], o0[3]); w.z = cvtpk(o1[0], o1[1]); w.w = cvtpk(o1[2], o1[3]);
.LBB0_628:
	s_lshr_b32 s4, s25, 5
	s_mulk_i32 s4, 0x2400
	s_ashr_i32 s5, s4, 31
	s_lshl_b64 s[4:5], s[4:5], 2
	s_add_u32 s4, s38, s4
	v_lshl_or_b32 v2, s40, 8, v178
	s_addc_u32 s5, s18, s5
	v_ashrrev_i32_e32 v3, 31, v2
	v_lshl_add_u64 v[134:135], v[2:3], 2, s[4:5]
	s_mov_b64 s[4:5], 0x2000
	v_lshl_add_u64 v[138:139], v[134:135], 0, s[4:5]
	v_add_co_u32_e32 v134, vcc, s47, v134
	v_add_u32_e32 v170, s42, v176
	s_nop 0
	v_addc_co_u32_e32 v135, vcc, 0, v135, vcc
	global_load_dwordx4 v[146:149], v[134:135], off
	s_nop 0
	global_load_dwordx4 v[134:137], v[138:139], off offset:528
	global_load_dwordx4 v[142:145], v[138:139], off offset:16
	s_nop 0
	global_load_dwordx4 v[138:141], v[138:139], off offset:512
	v_ashrrev_i32_e32 v171, 31, v170
	v_lshlrev_b64 v[150:151], 10, v[170:171]
	v_lshl_add_u64 v[150:151], v[150:151], 0, v[2:3]
	v_lshl_add_u64 v[2:3], v[150:151], 1, s[56:57]
	v_lshl_add_u64 v[174:175], v[150:151], 2, s[64:65]
	v_mov_b64_e32 v[182:183], v[2:3]
	s_andn2_b64 vcc, exec, s[66:67]
	s_cbranch_vccnz .Lres_epi_bf16
	s_mov_b32 s4, 0x10000
	s_mov_b32 s5, 0
	s_mov_b32 vcc_lo, 0x50000
	s_mov_b32 vcc_hi, 0
	global_load_dwordx4 v[150:153], v[174:175], off nt
	global_load_dwordx4 v[154:157], v[174:175], off offset:16 nt
	global_load_dwordx4 v[170:173], v[174:175], off offset:512 nt
	global_load_dwordx4 v[184:187], v[174:175], off offset:528 nt
	v_lshl_add_u64 v[174:175], v[174:175], 0, s[4:5]
	global_load_dwordx4 v[188:191], v[174:175], off nt
	global_load_dwordx4 v[192:195], v[174:175], off offset:16 nt
	global_load_dwordx4 v[208:211], v[174:175], off offset:512 nt
	global_load_dwordx4 v[226:229], v[174:175], off offset:528 nt
	v_lshl_add_u64 v[174:175], v[174:175], 0, s[4:5]
	global_load_dwordx4 v[230:233], v[174:175], off nt
	global_load_dwordx4 v[234:237], v[174:175], off offset:16 nt
	global_load_dwordx4 v[238:241], v[174:175], off offset:512 nt
	global_load_dwordx4 v[242:245], v[174:175], off offset:528 nt
	v_lshl_add_u64 v[174:175], v[174:175], 0, s[4:5]
	global_load_dwordx4 v[246:249], v[174:175], off nt
	global_load_dwordx4 v[250:253], v[174:175], off offset:16 nt
	s_waitcnt vmcnt(12)
	v_pk_add_f32 v[148:149], v[148:149], 1.0 op_sel_hi:[1,0]
	v_pk_add_f32 v[180:181], v[146:147], 1.0 op_sel_hi:[1,0]
	v_pk_mul_f32 v[146:147], s[60:61], v[148:149]
	v_pk_mul_f32 v[148:149], s[10:11], v[180:181]
	v_pk_add_f32 v[180:181], v[142:143], 1.0 op_sel_hi:[1,0]
	v_pk_add_f32 v[142:143], v[144:145], 1.0 op_sel_hi:[1,0]
	v_pk_mul_f32 v[144:145], s[10:11], v[180:181]
	v_pk_mul_f32 v[142:143], s[60:61], v[142:143]
	v_pk_add_f32 v[140:141], v[140:141], 1.0 op_sel_hi:[1,0]
	v_pk_add_f32 v[180:181], v[138:139], 1.0 op_sel_hi:[1,0]
	v_pk_mul_f32 v[138:139], s[60:61], v[140:141]
	v_pk_mul_f32 v[140:141], s[10:11], v[180:181]
	v_pk_add_f32 v[180:181], v[134:135], 1.0 op_sel_hi:[1,0]
	v_pk_add_f32 v[134:135], v[136:137], 1.0 op_sel_hi:[1,0]
	v_pk_mul_f32 v[136:137], s[10:11], v[180:181]
	v_pk_mul_f32 v[134:135], s[60:61], v[134:135]
	v_pk_fma_f32 v[130:131], v[130:131], v[148:149], v[150:151]
	v_pk_fma_f32 v[132:133], v[132:133], v[146:147], v[152:153]
	v_pk_fma_f32 v[126:127], v[126:127], v[144:145], v[154:155]
	v_pk_fma_f32 v[128:129], v[128:129], v[142:143], v[156:157]
	v_cvt_pk_bf16_f32 v130, v130, v131
	v_cvt_pk_bf16_f32 v131, v132, v133
	v_cvt_pk_bf16_f32 v132, v126, v127
	v_cvt_pk_bf16_f32 v133, v128, v129
	global_load_dwordx4 v[150:153], v[174:175], off offset:512 nt
	global_load_dwordx4 v[154:157], v[174:175], off offset:528 nt
	v_lshl_add_u64 v[174:175], v[174:175], 0, vcc
	s_waitcnt vmcnt(12)
	v_pk_fma_f32 v[122:123], v[122:123], v[140:141], v[170:171]
	v_pk_fma_f32 v[124:125], v[124:125], v[138:139], v[172:173]
	v_pk_fma_f32 v[118:119], v[118:119], v[136:137], v[184:185]
	v_pk_fma_f32 v[120:121], v[120:121], v[134:135], v[186:187]
	v_cvt_pk_bf16_f32 v122, v122, v123
	v_cvt_pk_bf16_f32 v123, v124, v125
	v_cvt_pk_bf16_f32 v124, v118, v119
	v_cvt_pk_bf16_f32 v125, v120, v121
	global_load_dwordx4 v[126:129], v[174:175], off nt
	global_load_dwordx4 v[170:173], v[174:175], off offset:16 nt
	global_load_dwordx4 v[184:187], v[174:175], off offset:512 nt
	global_load_dwordx4 v[118:121], v[174:175], off offset:528 nt
	v_lshl_add_u64 v[174:175], v[174:175], 0, s[4:5]
	s_waitcnt vmcnt(14)
	v_pk_fma_f32 v[114:115], v[114:115], v[148:149], v[188:189]
	v_pk_fma_f32 v[116:117], v[116:117], v[146:147], v[190:191]
	v_pk_fma_f32 v[110:111], v[110:111], v[144:145], v[192:193]
	v_pk_fma_f32 v[112:113], v[112:113], v[142:143], v[194:195]
	v_cvt_pk_bf16_f32 v114, v114, v115
	v_cvt_pk_bf16_f32 v115, v116, v117
	v_cvt_pk_bf16_f32 v116, v110, v111
	v_cvt_pk_bf16_f32 v117, v112, v113
	global_load_dwordx4 v[188:191], v[174:175], off nt
	global_load_dwordx4 v[192:195], v[174:175], off offset:16 nt
	s_waitcnt vmcnt(14)
	v_pk_fma_f32 v[106:107], v[106:107], v[140:141], v[208:209]
	v_pk_fma_f32 v[108:109], v[108:109], v[138:139], v[210:211]
	v_pk_fma_f32 v[102:103], v[102:103], v[136:137], v[226:227]
	v_pk_fma_f32 v[104:105], v[104:105], v[134:135], v[228:229]
	v_cvt_pk_bf16_f32 v106, v106, v107
	v_cvt_pk_bf16_f32 v107, v108, v109
	v_cvt_pk_bf16_f32 v108, v102, v103
	v_cvt_pk_bf16_f32 v109, v104, v105
	global_load_dwordx4 v[110:113], v[174:175], off offset:512 nt
	global_load_dwordx4 v[208:211], v[174:175], off offset:528 nt
	v_lshl_add_u64 v[174:175], v[174:175], 0, s[4:5]
	global_load_dwordx4 v[226:229], v[174:175], off nt
	global_load_dwordx4 v[102:105], v[174:175], off offset:16 nt
	s_waitcnt vmcnt(16)
; #define PG8_GAS __attribute__((address_space(1)))
; __device__ __forceinline__ unsigned cvtpk(float lo, float hi) { f32x2 v = {lo, hi}; bf16x2_t b = __builtin_convertvector(v, bf16x2_t); return __builtin_bit_cast(unsigned, b); }
;     __device__ __forceinline__ void operator()(const f32x4 (&acc)[2][2][4][2], const Unit& u, int wr, int wc, int fr, int fq) const {
;     ...
;                 for (int bj = 0; bj < 2; ++bj) {
;                     f32x4 b0, b1;
;                     if (basef) { b0 = __builtin_nontemporal_load((const PG8_GAS f32x4*)(basef + off + bj * HALF)); b1 = __builtin_nontemporal_load((const PG8_GAS f32x4*)(basef + off + bj * HALF + 4)); }
;                     else { const u32x4 w = __builtin_nontemporal_load((const PG8_GAS u32x4*)(baseb + off + bj * HALF));
;                         b0 = (f32x4){__uint_as_float(w.x << 16), __uint_as_float(w.x & 0xffff0000u), __uint_as_float(w.y << 16), __uint_as_float(w.y & 0xffff0000u)};
;                         b1 = (f32x4){__uint_as_float(w.z << 16), __uint_as_float(w.z & 0xffff0000u), __uint_as_float(w.w << 16), __uint_as_float(w.w & 0xffff0000u)}; }
;                     const f32x4 o0 = b0 + gv[bj][0] * acc[ai][bj][m][0], o1 = b1 + gv[bj][1] * acc[ai][bj][m][1];
;                     u32x4 w; w.x = cvtpk(o0[0], o0[1]); w.y = cvtpk(o0[2], o0[3]); w.z = cvtpk(o1[0], o1[1]); w.w = cvtpk(o1[2], o1[3]);
;                     __builtin_nontemporal_store(w, (PG8_GAS u32x4*)(out + off + bj * HALF));
	v_pk_fma_f32 v[98:99], v[98:99], v[148:149], v[230:231]
	v_pk_fma_f32 v[100:101], v[100:101], v[146:147], v[232:233]
	v_pk_fma_f32 v[94:95], v[94:95], v[144:145], v[234:235]
	v_pk_fma_f32 v[96:97], v[96:97], v[142:143], v[236:237]
	v_cvt_pk_bf16_f32 v98, v98, v99
	v_cvt_pk_bf16_f32 v99, v100, v101
	v_cvt_pk_bf16_f32 v100, v94, v95
	v_cvt_pk_bf16_f32 v101, v96, v97
	global_load_dwordx4 v[230:233], v[174:175], off offset:512 nt
	global_load_dwordx4 v[234:237], v[174:175], off offset:528 nt
	v_lshl_add_u64 v[174:175], v[174:175], 0, s[4:5]
	s_waitcnt vmcnt(16)
	v_pk_fma_f32 v[90:91], v[90:91], v[140:141], v[238:239]
	v_pk_fma_f32 v[92:93], v[92:93], v[138:139], v[240:241]
	v_pk_fma_f32 v[86:87], v[86:87], v[136:137], v[242:243]
	v_pk_fma_f32 v[88:89], v[88:89], v[134:135], v[244:245]
	v_cvt_pk_bf16_f32 v90, v90, v91
	v_cvt_pk_bf16_f32 v91, v92, v93
	v_cvt_pk_bf16_f32 v92, v86, v87
	v_cvt_pk_bf16_f32 v93, v88, v89
	global_load_dwordx4 v[94:97], v[174:175], off nt
	global_load_dwordx4 v[238:241], v[174:175], off offset:16 nt
	global_load_dwordx4 v[242:245], v[174:175], off offset:512 nt
	global_load_dwordx4 v[86:89], v[174:175], off offset:528 nt
	s_mov_b32 s4, 0x8000
	s_mov_b32 vcc_lo, 0x28000
	global_store_dwordx4 v[2:3], v[130:133], off sc1
	global_store_dwordx4 v[2:3], v[122:125], off offset:256 sc1
	v_lshl_add_u64 v[2:3], v[2:3], 0, s[4:5]
	global_store_dwordx4 v[2:3], v[114:117], off sc1
	global_store_dwordx4 v[2:3], v[106:109], off offset:256 sc1
	v_lshl_add_u64 v[2:3], v[2:3], 0, s[4:5]
	global_store_dwordx4 v[2:3], v[98:101], off sc1
	global_store_dwordx4 v[2:3], v[90:93], off offset:256 sc1
	v_lshl_add_u64 v[2:3], v[2:3], 0, s[4:5]
	s_waitcnt vmcnt(24)
	v_pk_fma_f32 v[82:83], v[82:83], v[148:149], v[246:247]
	v_pk_fma_f32 v[84:85], v[84:85], v[146:147], v[248:249]
	v_pk_fma_f32 v[78:79], v[78:79], v[144:145], v[250:251]
	v_pk_fma_f32 v[80:81], v[80:81], v[142:143], v[252:253]
	v_cvt_pk_bf16_f32 v82, v82, v83
	v_cvt_pk_bf16_f32 v83, v84, v85
	v_cvt_pk_bf16_f32 v84, v78, v79
	v_cvt_pk_bf16_f32 v85, v80, v81
	global_store_dwordx4 v[2:3], v[82:85], off sc1
	s_waitcnt vmcnt(23)
	v_pk_fma_f32 v[74:75], v[74:75], v[140:141], v[150:151]
	v_pk_fma_f32 v[76:77], v[76:77], v[138:139], v[152:153]
	v_pk_fma_f32 v[70:71], v[70:71], v[136:137], v[154:155]
	v_pk_fma_f32 v[72:73], v[72:73], v[134:135], v[156:157]
	v_cvt_pk_bf16_f32 v74, v74, v75
	v_cvt_pk_bf16_f32 v75, v76, v77
	v_cvt_pk_bf16_f32 v76, v70, v71
	v_cvt_pk_bf16_f32 v77, v72, v73
	global_store_dwordx4 v[2:3], v[74:77], off offset:256 sc1
	v_lshl_add_u64 v[2:3], v[2:3], 0, vcc
	s_waitcnt vmcnt(22)
	v_pk_fma_f32 v[66:67], v[66:67], v[148:149], v[126:127]
	v_pk_fma_f32 v[68:69], v[68:69], v[146:147], v[128:129]
	v_pk_fma_f32 v[62:63], v[62:63], v[144:145], v[170:171]
	v_pk_fma_f32 v[64:65], v[64:65], v[142:143], v[172:173]
	v_cvt_pk_bf16_f32 v66, v66, v67
	v_cvt_pk_bf16_f32 v67, v68, v69
	v_cvt_pk_bf16_f32 v68, v62, v63
	v_cvt_pk_bf16_f32 v69, v64, v65
	global_store_dwordx4 v[2:3], v[66:69], off sc1
	s_waitcnt vmcnt(21)
	v_pk_fma_f32 v[58:59], v[58:59], v[140:141], v[184:185]
	v_pk_fma_f32 v[60:61], v[60:61], v[138:139], v[186:187]
	v_pk_fma_f32 v[54:55], v[54:55], v[136:137], v[118:119]
	v_pk_fma_f32 v[56:57], v[56:57], v[134:135], v[120:121]
	v_cvt_pk_bf16_f32 v58, v58, v59
	v_cvt_pk_bf16_f32 v59, v60, v61
	v_cvt_pk_bf16_f32 v60, v54, v55
	v_cvt_pk_bf16_f32 v61, v56, v57
	global_store_dwordx4 v[2:3], v[58:61], off offset:256 sc1
	v_lshl_add_u64 v[2:3], v[2:3], 0, s[4:5]
	s_waitcnt vmcnt(20)
	v_pk_fma_f32 v[50:51], v[50:51], v[148:149], v[188:189]
	v_pk_fma_f32 v[52:53], v[52:53], v[146:147], v[190:191]
	v_pk_fma_f32 v[46:47], v[46:47], v[144:145], v[192:193]
	v_pk_fma_f32 v[48:49], v[48:49], v[142:143], v[194:195]
	v_cvt_pk_bf16_f32 v50, v50, v51
	v_cvt_pk_bf16_f32 v51, v52, v53
	v_cvt_pk_bf16_f32 v52, v46, v47
	v_cvt_pk_bf16_f32 v53, v48, v49
	global_store_dwordx4 v[2:3], v[50:53], off sc1
	s_waitcnt vmcnt(19)
	v_pk_fma_f32 v[42:43], v[42:43], v[140:141], v[110:111]
	v_pk_fma_f32 v[44:45], v[44:45], v[138:139], v[112:113]
	v_pk_fma_f32 v[38:39], v[38:39], v[136:137], v[208:209]
	v_pk_fma_f32 v[40:41], v[40:41], v[134:135], v[210:211]
	v_cvt_pk_bf16_f32 v42, v42, v43
	v_cvt_pk_bf16_f32 v43, v44, v45
	v_cvt_pk_bf16_f32 v44, v38, v39
	v_cvt_pk_bf16_f32 v45, v40, v41
	global_store_dwordx4 v[2:3], v[42:45], off offset:256 sc1
	v_lshl_add_u64 v[2:3], v[2:3], 0, s[4:5]
	s_waitcnt vmcnt(18)
	v_pk_fma_f32 v[34:35], v[34:35], v[148:149], v[226:227]
	v_pk_fma_f32 v[36:37], v[36:37], v[146:147], v[228:229]
	v_pk_fma_f32 v[30:31], v[30:31], v[144:145], v[102:103]
	v_pk_fma_f32 v[32:33], v[32:33], v[142:143], v[104:105]
	v_cvt_pk_bf16_f32 v34, v34, v35
	v_cvt_pk_bf16_f32 v35, v36, v37
	v_cvt_pk_bf16_f32 v36, v30, v31
	v_cvt_pk_bf16_f32 v37, v32, v33
	global_store_dwordx4 v[2:3], v[34:37], off sc1
	s_waitcnt vmcnt(17)
	v_pk_fma_f32 v[26:27], v[26:27], v[140:141], v[230:231]
	v_pk_fma_f32 v[28:29], v[28:29], v[138:139], v[232:233]
	v_pk_fma_f32 v[22:23], v[22:23], v[136:137], v[234:235]
	v_pk_fma_f32 v[24:25], v[24:25], v[134:135], v[236:237]
	v_cvt_pk_bf16_f32 v26, v26, v27
	v_cvt_pk_bf16_f32 v27, v28, v29
	v_cvt_pk_bf16_f32 v28, v22, v23
	v_cvt_pk_bf16_f32 v29, v24, v25
	global_store_dwordx4 v[2:3], v[26:29], off offset:256 sc1
	v_lshl_add_u64 v[2:3], v[2:3], 0, s[4:5]
	s_waitcnt vmcnt(16)
	v_pk_fma_f32 v[18:19], v[18:19], v[148:149], v[94:95]
	v_pk_fma_f32 v[20:21], v[20:21], v[146:147], v[96:97]
	v_pk_fma_f32 v[14:15], v[14:15], v[144:145], v[238:239]
	v_pk_fma_f32 v[16:17], v[16:17], v[142:143], v[240:241]
	v_cvt_pk_bf16_f32 v18, v18, v19
	v_cvt_pk_bf16_f32 v19, v20, v21
	v_cvt_pk_bf16_f32 v20, v14, v15
	v_cvt_pk_bf16_f32 v21, v16, v17
	global_store_dwordx4 v[2:3], v[18:21], off sc1
	s_waitcnt vmcnt(15)
	v_pk_fma_f32 v[10:11], v[10:11], v[140:141], v[242:243]
	v_pk_fma_f32 v[12:13], v[12:13], v[138:139], v[244:245]
	v_pk_fma_f32 v[6:7], v[6:7], v[136:137], v[86:87]
	v_pk_fma_f32 v[8:9], v[8:9], v[134:135], v[88:89]
	v_cvt_pk_bf16_f32 v10, v10, v11
	v_cvt_pk_bf16_f32 v11, v12, v13
	v_cvt_pk_bf16_f32 v12, v6, v7
	v_cvt_pk_bf16_f32 v13, v8, v9
	s_and_b64 vcc, exec, s[6:7]
	s_mov_b64 s[4:5], -1
	global_store_dwordx4 v[2:3], v[10:13], off offset:256 sc1
	s_branch .Lres_epi_tail
; #define PG8_GAS __attribute__((address_space(1)))
; __device__ __forceinline__ unsigned cvtpk(float lo, float hi) { f32x2 v = {lo, hi}; bf16x2_t b = __builtin_convertvector(v, bf16x2_t); return __builtin_bit_cast(unsigned, b); }
; template <class T> __device__ __forceinline__ GAS T* gp(T* p) { return (GAS T*)p; }
;     __device__ __forceinline__ void operator()(const f32x4 (&acc)[2][2][4][2], const Unit& u, int wr, int wc, int fr, int fq) const {
;     ...
;         for (int bj = 0; bj < 2; ++bj)
; #pragma unroll
;             for (int n = 0; n < 2; ++n) gv[bj][n] = (*(const PG8_GAS f32x4*)(gp + col0 + bj * HALF + 4 * n) + 1.0f) * coef;
; #pragma unroll
;         for (int ai = 0; ai < 2; ++ai)
; #pragma unroll
;             for (int m = 0; m < 4; ++m) {
;                 const size_t off = (size_t)(u.pm * BM + ai * HALF + wr * 64 + m * 16 + fr) * 1024 + col0;
; #pragma unroll
;                 for (int bj = 0; bj < 2; ++bj) {
;                     f32x4 b0, b1;
;                     if (basef) { b0 = __builtin_nontemporal_load((const PG8_GAS f32x4*)(basef + off + bj * HALF)); b1 = __builtin_nontemporal_load((const PG8_GAS f32x4*)(basef + off + bj * HALF + 4)); }
;                     else { const u32x4 w = __builtin_nontemporal_load((const PG8_GAS u32x4*)(baseb + off + bj * HALF));
;                         b0 = (f32x4){__uint_as_float(w.x << 16), __uint_as_float(w.x & 0xffff0000u), __uint_as_float(w.y << 16), __uint_as_float(w.y & 0xffff0000u)};
;                         b1 = (f32x4){__uint_as_float(w.z << 16), __uint_as_float(w.z & 0xffff0000u), __uint_as_float(w.w << 16), __uint_as_float(w.w & 0xffff0000u)}; }
;                     const f32x4 o0 = b0 + gv[bj][0] * acc[ai][bj][m][0], o1 = b1 + gv[bj][1] * acc[ai][bj][m][1];
;                     u32x4 w; w.x = cvtpk(o0[0], o0[1]); w.y = cvtpk(o0[2], o0[3]); w.z = cvtpk(o1[0], o1[1]); w.w = cvtpk(o1[2], o1[3]);
;                     __builtin_nontemporal_store(w, (PG8_GAS u32x4*)(out + off + bj * HALF));
.Lres_epi_bf16:
	s_mov_b32 s4, 0x8000
	s_mov_b32 s5, 0
	s_mov_b32 vcc_lo, 0x28000
	s_mov_b32 vcc_hi, 0
	global_load_dwordx4 v[150:153], v[182:183], off nt
	global_load_dwordx4 v[154:157], v[182:183], off offset:256 nt
	v_lshl_add_u64 v[182:183], v[182:183], 0, s[4:5]
	global_load_dwordx4 v[170:173], v[182:183], off nt
	global_load_dwordx4 v[184:187], v[182:183], off offset:256 nt
	v_lshl_add_u64 v[182:183], v[182:183], 0, s[4:5]
	global_load_dwordx4 v[188:191], v[182:183], off nt
	global_load_dwordx4 v[192:195], v[182:183], off offset:256 nt
	v_lshl_add_u64 v[182:183], v[182:183], 0, s[4:5]
	global_load_dwordx4 v[208:211], v[182:183], off nt
	global_load_dwordx4 v[226:229], v[182:183], off offset:256 nt
	v_lshl_add_u64 v[182:183], v[182:183], 0, vcc
	global_load_dwordx4 v[230:233], v[182:183], off nt
	global_load_dwordx4 v[234:237], v[182:183], off offset:256 nt
	v_lshl_add_u64 v[182:183], v[182:183], 0, s[4:5]
	global_load_dwordx4 v[238:241], v[182:183], off nt
	global_load_dwordx4 v[242:245], v[182:183], off offset:256 nt
	v_lshl_add_u64 v[182:183], v[182:183], 0, s[4:5]
	global_load_dwordx4 v[246:249], v[182:183], off nt
	global_load_dwordx4 v[250:253], v[182:183], off offset:256 nt
	v_lshl_add_u64 v[182:183], v[182:183], 0, s[4:5]
	s_waitcnt vmcnt(13)
	v_pk_add_f32 v[148:149], v[148:149], 1.0 op_sel_hi:[1,0]
	v_pk_add_f32 v[180:181], v[146:147], 1.0 op_sel_hi:[1,0]
	v_pk_mul_f32 v[146:147], s[60:61], v[148:149]
	v_pk_mul_f32 v[148:149], s[10:11], v[180:181]
	v_pk_add_f32 v[180:181], v[142:143], 1.0 op_sel_hi:[1,0]
	v_pk_add_f32 v[142:143], v[144:145], 1.0 op_sel_hi:[1,0]
	v_pk_mul_f32 v[144:145], s[10:11], v[180:181]
	v_pk_mul_f32 v[142:143], s[60:61], v[142:143]
	v_pk_add_f32 v[140:141], v[140:141], 1.0 op_sel_hi:[1,0]
	v_pk_add_f32 v[180:181], v[138:139], 1.0 op_sel_hi:[1,0]
	v_pk_mul_f32 v[138:139], s[60:61], v[140:141]
	v_pk_mul_f32 v[140:141], s[10:11], v[180:181]
	v_pk_add_f32 v[180:181], v[134:135], 1.0 op_sel_hi:[1,0]
	v_pk_add_f32 v[134:135], v[136:137], 1.0 op_sel_hi:[1,0]
	v_pk_mul_f32 v[136:137], s[10:11], v[180:181]
	v_pk_mul_f32 v[134:135], s[60:61], v[134:135]
	v_lshlrev_b32_e32 v180, 16, v150
	v_and_b32_e32 v181, 0xffff0000, v150
	v_pk_fma_f32 v[130:131], v[130:131], v[148:149], v[180:181]
	v_lshlrev_b32_e32 v150, 16, v151
	v_and_b32_e32 v151, 0xffff0000, v151
	v_pk_fma_f32 v[132:133], v[132:133], v[146:147], v[150:151]
	v_lshlrev_b32_e32 v180, 16, v152
	v_and_b32_e32 v181, 0xffff0000, v152
	v_pk_fma_f32 v[126:127], v[126:127], v[144:145], v[180:181]
	v_lshlrev_b32_e32 v152, 16, v153
	v_and_b32_e32 v153, 0xffff0000, v153
	v_pk_fma_f32 v[128:129], v[128:129], v[142:143], v[152:153]
	v_cvt_pk_bf16_f32 v130, v130, v131
	v_cvt_pk_bf16_f32 v131, v132, v133
	v_cvt_pk_bf16_f32 v132, v126, v127
	v_cvt_pk_bf16_f32 v133, v128, v129
	global_load_dwordx4 v[150:153], v[182:183], off nt
	global_load_dwordx4 v[126:129], v[182:183], off offset:256 nt
	global_store_dwordx4 v[2:3], v[130:133], off sc1
	s_waitcnt vmcnt(15)
	v_lshlrev_b32_e32 v180, 16, v154
	v_and_b32_e32 v181, 0xffff0000, v154
	v_pk_fma_f32 v[122:123], v[122:123], v[140:141], v[180:181]
	v_lshlrev_b32_e32 v154, 16, v155
	v_and_b32_e32 v155, 0xffff0000, v155
	v_pk_fma_f32 v[124:125], v[124:125], v[138:139], v[154:155]
	v_lshlrev_b32_e32 v180, 16, v156
	v_and_b32_e32 v181, 0xffff0000, v156
	v_pk_fma_f32 v[118:119], v[118:119], v[136:137], v[180:181]
	v_lshlrev_b32_e32 v156, 16, v157
	v_and_b32_e32 v157, 0xffff0000, v157
	v_pk_fma_f32 v[120:121], v[120:121], v[134:135], v[156:157]
	v_cvt_pk_bf16_f32 v122, v122, v123
	v_cvt_pk_bf16_f32 v123, v124, v125
	v_cvt_pk_bf16_f32 v124, v118, v119
	v_cvt_pk_bf16_f32 v125, v120, v121
	global_store_dwordx4 v[2:3], v[122:125], off offset:256 sc1
	v_lshl_add_u64 v[2:3], v[2:3], 0, s[4:5]
	s_waitcnt vmcnt(15)
	v_lshlrev_b32_e32 v180, 16, v170
	v_and_b32_e32 v181, 0xffff0000, v170
	v_pk_fma_f32 v[114:115], v[114:115], v[148:149], v[180:181]
	v_lshlrev_b32_e32 v170, 16, v171
	v_and_b32_e32 v171, 0xffff0000, v171
	v_pk_fma_f32 v[116:117], v[116:117], v[146:147], v[170:171]
	v_lshlrev_b32_e32 v180, 16, v172
	v_and_b32_e32 v181, 0xffff0000, v172
	v_pk_fma_f32 v[110:111], v[110:111], v[144:145], v[180:181]
	v_lshlrev_b32_e32 v172, 16, v173
	v_and_b32_e32 v173, 0xffff0000, v173
	v_pk_fma_f32 v[112:113], v[112:113], v[142:143], v[172:173]
	v_cvt_pk_bf16_f32 v114, v114, v115
	v_cvt_pk_bf16_f32 v115, v116, v117
	v_cvt_pk_bf16_f32 v116, v110, v111
	v_cvt_pk_bf16_f32 v117, v112, v113
	global_store_dwordx4 v[2:3], v[114:117], off sc1
	s_waitcnt vmcnt(15)
	v_lshlrev_b32_e32 v180, 16, v184
	v_and_b32_e32 v181, 0xffff0000, v184
	v_pk_fma_f32 v[106:107], v[106:107], v[140:141], v[180:181]
	v_lshlrev_b32_e32 v184, 16, v185
	v_and_b32_e32 v185, 0xffff0000, v185
	v_pk_fma_f32 v[108:109], v[108:109], v[138:139], v[184:185]
	v_lshlrev_b32_e32 v180, 16, v186
	v_and_b32_e32 v181, 0xffff0000, v186
	v_pk_fma_f32 v[102:103], v[102:103], v[136:137], v[180:181]
	v_lshlrev_b32_e32 v186, 16, v187
	v_and_b32_e32 v187, 0xffff0000, v187
	v_pk_fma_f32 v[104:105], v[104:105], v[134:135], v[186:187]
	v_cvt_pk_bf16_f32 v106, v106, v107
	v_cvt_pk_bf16_f32 v107, v108, v109
	v_cvt_pk_bf16_f32 v108, v102, v103
	v_cvt_pk_bf16_f32 v109, v104, v105
	global_store_dwordx4 v[2:3], v[106:109], off offset:256 sc1
	v_lshl_add_u64 v[2:3], v[2:3], 0, s[4:5]
	s_waitcnt vmcnt(15)
; #define PG8_GAS __attribute__((address_space(1)))
; __device__ __forceinline__ unsigned cvtpk(float lo, float hi) { f32x2 v = {lo, hi}; bf16x2_t b = __builtin_convertvector(v, bf16x2_t); return __builtin_bit_cast(unsigned, b); }
;     __device__ __forceinline__ void operator()(const f32x4 (&acc)[2][2][4][2], const Unit& u, int wr, int wc, int fr, int fq) const {
;     ...
;                     else { const u32x4 w = __builtin_nontemporal_load((const PG8_GAS u32x4*)(baseb + off + bj * HALF));
;                         b0 = (f32x4){__uint_as_float(w.x << 16), __uint_as_float(w.x & 0xffff0000u), __uint_as_float(w.y << 16), __uint_as_float(w.y & 0xffff0000u)};
;                         b1 = (f32x4){__uint_as_float(w.z << 16), __uint_as_float(w.z & 0xffff0000u), __uint_as_float(w.w << 16), __uint_as_float(w.w & 0xffff0000u)}; }
;                     const f32x4 o0 = b0 + gv[bj][0] * acc[ai][bj][m][0], o1 = b1 + gv[bj][1] * acc[ai][bj][m][1];
;                     u32x4 w; w.x = cvtpk(o0[0], o0[1]); w.y = cvtpk(o0[2], o0[3]); w.z = cvtpk(o1[0], o1[1]); w.w = cvtpk(o1[2], o1[3]);
;                     __builtin_nontemporal_store(w, (PG8_GAS u32x4*)(out + off + bj * HALF));
	v_lshlrev_b32_e32 v180, 16, v188
	v_and_b32_e32 v181, 0xffff0000, v188
	v_pk_fma_f32 v[98:99], v[98:99], v[148:149], v[180:181]
	v_lshlrev_b32_e32 v188, 16, v189
	v_and_b32_e32 v189, 0xffff0000, v189
	v_pk_fma_f32 v[100:101], v[100:101], v[146:147], v[188:189]
	v_lshlrev_b32_e32 v180, 16, v190
	v_and_b32_e32 v181, 0xffff0000, v190
	v_pk_fma_f32 v[94:95], v[94:95], v[144:145], v[180:181]
	v_lshlrev_b32_e32 v190, 16, v191
	v_and_b32_e32 v191, 0xffff0000, v191
	v_pk_fma_f32 v[96:97], v[96:97], v[142:143], v[190:191]
	v_cvt_pk_bf16_f32 v98, v98, v99
	v_cvt_pk_bf16_f32 v99, v100, v101
	v_cvt_pk_bf16_f32 v100, v94, v95
	v_cvt_pk_bf16_f32 v101, v96, v97
	global_store_dwordx4 v[2:3], v[98:101], off sc1
	s_waitcnt vmcnt(15)
	v_lshlrev_b32_e32 v180, 16, v192
	v_and_b32_e32 v181, 0xffff0000, v192
	v_pk_fma_f32 v[90:91], v[90:91], v[140:141], v[180:181]
	v_lshlrev_b32_e32 v192, 16, v193
	v_and_b32_e32 v193, 0xffff0000, v193
	v_pk_fma_f32 v[92:93], v[92:93], v[138:139], v[192:193]
	v_lshlrev_b32_e32 v180, 16, v194
	v_and_b32_e32 v181, 0xffff0000, v194
	v_pk_fma_f32 v[86:87], v[86:87], v[136:137], v[180:181]
	v_lshlrev_b32_e32 v194, 16, v195
	v_and_b32_e32 v195, 0xffff0000, v195
	v_pk_fma_f32 v[88:89], v[88:89], v[134:135], v[194:195]
	v_cvt_pk_bf16_f32 v90, v90, v91
	v_cvt_pk_bf16_f32 v91, v92, v93
	v_cvt_pk_bf16_f32 v92, v86, v87
	v_cvt_pk_bf16_f32 v93, v88, v89
	global_store_dwordx4 v[2:3], v[90:93], off offset:256 sc1
	v_lshl_add_u64 v[2:3], v[2:3], 0, s[4:5]
	s_waitcnt vmcnt(15)
	v_lshlrev_b32_e32 v180, 16, v208
	v_and_b32_e32 v181, 0xffff0000, v208
	v_pk_fma_f32 v[82:83], v[82:83], v[148:149], v[180:181]
	v_lshlrev_b32_e32 v208, 16, v209
	v_and_b32_e32 v209, 0xffff0000, v209
	v_pk_fma_f32 v[84:85], v[84:85], v[146:147], v[208:209]
	v_lshlrev_b32_e32 v180, 16, v210
	v_and_b32_e32 v181, 0xffff0000, v210
	v_pk_fma_f32 v[78:79], v[78:79], v[144:145], v[180:181]
	v_lshlrev_b32_e32 v210, 16, v211
	v_and_b32_e32 v211, 0xffff0000, v211
	v_pk_fma_f32 v[80:81], v[80:81], v[142:143], v[210:211]
	v_cvt_pk_bf16_f32 v82, v82, v83
	v_cvt_pk_bf16_f32 v83, v84, v85
	v_cvt_pk_bf16_f32 v84, v78, v79
	v_cvt_pk_bf16_f32 v85, v80, v81
	global_store_dwordx4 v[2:3], v[82:85], off sc1
	s_waitcnt vmcnt(15)
	v_lshlrev_b32_e32 v180, 16, v226
	v_and_b32_e32 v181, 0xffff0000, v226
	v_pk_fma_f32 v[74:75], v[74:75], v[140:141], v[180:181]
	v_lshlrev_b32_e32 v226, 16, v227
	v_and_b32_e32 v227, 0xffff0000, v227
	v_pk_fma_f32 v[76:77], v[76:77], v[138:139], v[226:227]
	v_lshlrev_b32_e32 v180, 16, v228
	v_and_b32_e32 v181, 0xffff0000, v228
	v_pk_fma_f32 v[70:71], v[70:71], v[136:137], v[180:181]
	v_lshlrev_b32_e32 v228, 16, v229
	v_and_b32_e32 v229, 0xffff0000, v229
	v_pk_fma_f32 v[72:73], v[72:73], v[134:135], v[228:229]
	v_cvt_pk_bf16_f32 v74, v74, v75
	v_cvt_pk_bf16_f32 v75, v76, v77
	v_cvt_pk_bf16_f32 v76, v70, v71
	v_cvt_pk_bf16_f32 v77, v72, v73
	global_store_dwordx4 v[2:3], v[74:77], off offset:256 sc1
	v_lshl_add_u64 v[2:3], v[2:3], 0, vcc
	s_waitcnt vmcnt(15)
	v_lshlrev_b32_e32 v180, 16, v230
	v_and_b32_e32 v181, 0xffff0000, v230
	v_pk_fma_f32 v[66:67], v[66:67], v[148:149], v[180:181]
	v_lshlrev_b32_e32 v230, 16, v231
	v_and_b32_e32 v231, 0xffff0000, v231
	v_pk_fma_f32 v[68:69], v[68:69], v[146:147], v[230:231]
	v_lshlrev_b32_e32 v180, 16, v232
	v_and_b32_e32 v181, 0xffff0000, v232
	v_pk_fma_f32 v[62:63], v[62:63], v[144:145], v[180:181]
	v_lshlrev_b32_e32 v232, 16, v233
	v_and_b32_e32 v233, 0xffff0000, v233
	v_pk_fma_f32 v[64:65], v[64:65], v[142:143], v[232:233]
	v_cvt_pk_bf16_f32 v66, v66, v67
	v_cvt_pk_bf16_f32 v67, v68, v69
	v_cvt_pk_bf16_f32 v68, v62, v63
	v_cvt_pk_bf16_f32 v69, v64, v65
	global_store_dwordx4 v[2:3], v[66:69], off sc1
	s_waitcnt vmcnt(15)
	v_lshlrev_b32_e32 v180, 16, v234
	v_and_b32_e32 v181, 0xffff0000, v234
	v_pk_fma_f32 v[58:59], v[58:59], v[140:141], v[180:181]
	v_lshlrev_b32_e32 v234, 16, v235
	v_and_b32_e32 v235, 0xffff0000, v235
	v_pk_fma_f32 v[60:61], v[60:61], v[138:139], v[234:235]
	v_lshlrev_b32_e32 v180, 16, v236
	v_and_b32_e32 v181, 0xffff0000, v236
	v_pk_fma_f32 v[54:55], v[54:55], v[136:137], v[180:181]
	v_lshlrev_b32_e32 v236, 16, v237
	v_and_b32_e32 v237, 0xffff0000, v237
	v_pk_fma_f32 v[56:57], v[56:57], v[134:135], v[236:237]
	v_cvt_pk_bf16_f32 v58, v58, v59
	v_cvt_pk_bf16_f32 v59, v60, v61
	v_cvt_pk_bf16_f32 v60, v54, v55
	v_cvt_pk_bf16_f32 v61, v56, v57
	global_store_dwordx4 v[2:3], v[58:61], off offset:256 sc1
	v_lshl_add_u64 v[2:3], v[2:3], 0, s[4:5]
	s_waitcnt vmcnt(15)
; #define PG8_GAS __attribute__((address_space(1)))
; __device__ __forceinline__ unsigned cvtpk(float lo, float hi) { f32x2 v = {lo, hi}; bf16x2_t b = __builtin_convertvector(v, bf16x2_t); return __builtin_bit_cast(unsigned, b); }
;     __device__ __forceinline__ void operator()(const f32x4 (&acc)[2][2][4][2], const Unit& u, int wr, int wc, int fr, int fq) const {
;     ...
;                     else { const u32x4 w = __builtin_nontemporal_load((const PG8_GAS u32x4*)(baseb + off + bj * HALF));
;                         b0 = (f32x4){__uint_as_float(w.x << 16), __uint_as_float(w.x & 0xffff0000u), __uint_as_float(w.y << 16), __uint_as_float(w.y & 0xffff0000u)};
;                         b1 = (f32x4){__uint_as_float(w.z << 16), __uint_as_float(w.z & 0xffff0000u), __uint_as_float(w.w << 16), __uint_as_float(w.w & 0xffff0000u)}; }
;                     const f32x4 o0 = b0 + gv[bj][0] * acc[ai][bj][m][0], o1 = b1 + gv[bj][1] * acc[ai][bj][m][1];
;                     u32x4 w; w.x = cvtpk(o0[0], o0[1]); w.y = cvtpk(o0[2], o0[3]); w.z = cvtpk(o1[0], o1[1]); w.w = cvtpk(o1[2], o1[3]);
;                     __builtin_nontemporal_store(w, (PG8_GAS u32x4*)(out + off + bj * HALF));
	v_lshlrev_b32_e32 v180, 16, v238
	v_and_b32_e32 v181, 0xffff0000, v238
	v_pk_fma_f32 v[50:51], v[50:51], v[148:149], v[180:181]
	v_lshlrev_b32_e32 v238, 16, v239
	v_and_b32_e32 v239, 0xffff0000, v239
	v_pk_fma_f32 v[52:53], v[52:53], v[146:147], v[238:239]
	v_lshlrev_b32_e32 v180, 16, v240
	v_and_b32_e32 v181, 0xffff0000, v240
	v_pk_fma_f32 v[46:47], v[46:47], v[144:145], v[180:181]
	v_lshlrev_b32_e32 v240, 16, v241
	v_and_b32_e32 v241, 0xffff0000, v241
	v_pk_fma_f32 v[48:49], v[48:49], v[142:143], v[240:241]
	v_cvt_pk_bf16_f32 v50, v50, v51
	v_cvt_pk_bf16_f32 v51, v52, v53
	v_cvt_pk_bf16_f32 v52, v46, v47
	v_cvt_pk_bf16_f32 v53, v48, v49
	global_store_dwordx4 v[2:3], v[50:53], off sc1
	s_waitcnt vmcnt(15)
	v_lshlrev_b32_e32 v180, 16, v242
	v_and_b32_e32 v181, 0xffff0000, v242
	v_pk_fma_f32 v[42:43], v[42:43], v[140:141], v[180:181]
	v_lshlrev_b32_e32 v242, 16, v243
	v_and_b32_e32 v243, 0xffff0000, v243
	v_pk_fma_f32 v[44:45], v[44:45], v[138:139], v[242:243]
	v_lshlrev_b32_e32 v180, 16, v244
	v_and_b32_e32 v181, 0xffff0000, v244
	v_pk_fma_f32 v[38:39], v[38:39], v[136:137], v[180:181]
	v_lshlrev_b32_e32 v244, 16, v245
	v_and_b32_e32 v245, 0xffff0000, v245
	v_pk_fma_f32 v[40:41], v[40:41], v[134:135], v[244:245]
	v_cvt_pk_bf16_f32 v42, v42, v43
	v_cvt_pk_bf16_f32 v43, v44, v45
	v_cvt_pk_bf16_f32 v44, v38, v39
	v_cvt_pk_bf16_f32 v45, v40, v41
	global_store_dwordx4 v[2:3], v[42:45], off offset:256 sc1
	v_lshl_add_u64 v[2:3], v[2:3], 0, s[4:5]
	s_waitcnt vmcnt(15)
	v_lshlrev_b32_e32 v180, 16, v246
	v_and_b32_e32 v181, 0xffff0000, v246
	v_pk_fma_f32 v[34:35], v[34:35], v[148:149], v[180:181]
	v_lshlrev_b32_e32 v246, 16, v247
	v_and_b32_e32 v247, 0xffff0000, v247
	v_pk_fma_f32 v[36:37], v[36:37], v[146:147], v[246:247]
	v_lshlrev_b32_e32 v180, 16, v248
	v_and_b32_e32 v181, 0xffff0000, v248
	v_pk_fma_f32 v[30:31], v[30:31], v[144:145], v[180:181]
	v_lshlrev_b32_e32 v248, 16, v249
	v_and_b32_e32 v249, 0xffff0000, v249
	v_pk_fma_f32 v[32:33], v[32:33], v[142:143], v[248:249]
	v_cvt_pk_bf16_f32 v34, v34, v35
	v_cvt_pk_bf16_f32 v35, v36, v37
	v_cvt_pk_bf16_f32 v36, v30, v31
	v_cvt_pk_bf16_f32 v37, v32, v33
	global_store_dwordx4 v[2:3], v[34:37], off sc1
	s_waitcnt vmcnt(15)
	v_lshlrev_b32_e32 v180, 16, v250
	v_and_b32_e32 v181, 0xffff0000, v250
	v_pk_fma_f32 v[26:27], v[26:27], v[140:141], v[180:181]
	v_lshlrev_b32_e32 v250, 16, v251
	v_and_b32_e32 v251, 0xffff0000, v251
	v_pk_fma_f32 v[28:29], v[28:29], v[138:139], v[250:251]
	v_lshlrev_b32_e32 v180, 16, v252
	v_and_b32_e32 v181, 0xffff0000, v252
	v_pk_fma_f32 v[22:23], v[22:23], v[136:137], v[180:181]
	v_lshlrev_b32_e32 v252, 16, v253
	v_and_b32_e32 v253, 0xffff0000, v253
	v_pk_fma_f32 v[24:25], v[24:25], v[134:135], v[252:253]
	v_cvt_pk_bf16_f32 v26, v26, v27
	v_cvt_pk_bf16_f32 v27, v28, v29
	v_cvt_pk_bf16_f32 v28, v22, v23
	v_cvt_pk_bf16_f32 v29, v24, v25
	global_store_dwordx4 v[2:3], v[26:29], off offset:256 sc1
	v_lshl_add_u64 v[2:3], v[2:3], 0, s[4:5]
	s_waitcnt vmcnt(15)
	v_lshlrev_b32_e32 v180, 16, v150
	v_and_b32_e32 v181, 0xffff0000, v150
	v_pk_fma_f32 v[18:19], v[18:19], v[148:149], v[180:181]
	v_lshlrev_b32_e32 v150, 16, v151
	v_and_b32_e32 v151, 0xffff0000, v151
	v_pk_fma_f32 v[20:21], v[20:21], v[146:147], v[150:151]
	v_lshlrev_b32_e32 v180, 16, v152
	v_and_b32_e32 v181, 0xffff0000, v152
	v_pk_fma_f32 v[14:15], v[14:15], v[144:145], v[180:181]
	v_lshlrev_b32_e32 v152, 16, v153
	v_and_b32_e32 v153, 0xffff0000, v153
	v_pk_fma_f32 v[16:17], v[16:17], v[142:143], v[152:153]
	v_cvt_pk_bf16_f32 v18, v18, v19
	v_cvt_pk_bf16_f32 v19, v20, v21
	v_cvt_pk_bf16_f32 v20, v14, v15
	v_cvt_pk_bf16_f32 v21, v16, v17
	global_store_dwordx4 v[2:3], v[18:21], off sc1
	s_waitcnt vmcnt(15)
	v_lshlrev_b32_e32 v180, 16, v126
	v_and_b32_e32 v181, 0xffff0000, v126
	v_pk_fma_f32 v[10:11], v[10:11], v[140:141], v[180:181]
	v_lshlrev_b32_e32 v126, 16, v127
	v_and_b32_e32 v127, 0xffff0000, v127
	v_pk_fma_f32 v[12:13], v[12:13], v[138:139], v[126:127]
	v_lshlrev_b32_e32 v180, 16, v128
	v_and_b32_e32 v181, 0xffff0000, v128
	v_pk_fma_f32 v[6:7], v[6:7], v[136:137], v[180:181]
	v_lshlrev_b32_e32 v128, 16, v129
	v_and_b32_e32 v129, 0xffff0000, v129
	v_pk_fma_f32 v[8:9], v[8:9], v[134:135], v[128:129]
	v_cvt_pk_bf16_f32 v10, v10, v11
	v_cvt_pk_bf16_f32 v11, v12, v13
	v_cvt_pk_bf16_f32 v12, v6, v7
	v_cvt_pk_bf16_f32 v13, v8, v9
	s_and_b64 vcc, exec, s[6:7]
	s_mov_b64 s[4:5], -1
	global_store_dwordx4 v[2:3], v[10:13], off offset:256 sc1
